# out0/out1 epilogue pass 1 software-pipelined: load destinations renamed into spare registers, loads two blocks ahead, counted vmcnt; MLA loop DMA addresses on SALU
# speedup vs baseline: 1.1188x; 1.0058x over previous
.LBB0_390:
	s_lshl_b32 s34, s15, 8
	v_mov_b32 v128, 0
	s_add_i32 s82, s57, s34
	v_lshlrev_b32_e32 v154, 3, v132
	v_or_b32_e32 v128, s2, v154
	s_ashr_i32 s2, s82, 13
	s_mul_i32 s34, s2, 0xc00
	s_ashr_i32 s35, s34, 31
	s_ashr_i32 s83, s82, 31
	s_lshl_b64 s[34:35], s[34:35], 2
	v_or_b32_e32 v136, s58, v128
	s_add_u32 s58, s28, s34
	v_or_b32_e32 v140, s82, v152
	s_addc_u32 s59, s29, s35
	v_ashrrev_i32_e32 v141, 31, v140
	v_lshl_add_u64 v[128:129], v[136:137], 2, s[58:59]
	v_lshlrev_b64 v[130:131], 10, v[140:141]
	s_movk_i32 s2, 0x2000
	v_lshl_add_u64 v[130:131], v[130:131], 0, v[136:137]
	v_add_co_u32_e32 v146, vcc, s2, v128
	v_lshlrev_b64 v[148:149], 2, v[130:131]
	s_nop 0
	v_addc_co_u32_e32 v147, vcc, 0, v129, vcc
	v_lshl_add_u64 v[142:143], v[128:129], 0, s[6:7]
	v_lshl_add_u64 v[138:139], s[36:37], 0, v[148:149]
	global_load_dwordx4 v[212:215], v[146:147], off
	global_load_dwordx4 v[216:219], v[138:139], off offset:16
	global_load_dwordx4 v[220:223], v[138:139], off
	global_load_dwordx4 v[224:227], v[142:143], off offset:16
	global_load_dwordx4 v[228:231], v[142:143], off offset:80
	global_load_dwordx4 v[232:235], v[142:143], off offset:64
	global_load_dwordx4 v[238:241], v[138:139], off offset:64
	global_load_dwordx4 v[242:245], v[138:139], off offset:80
	global_load_dwordx4 v[246:249], v[142:143], off offset:144
	global_load_dwordx4 v[250:253], v[142:143], off offset:128
	global_load_dwordx4 v[162:165], v[138:139], off offset:128
	global_load_dwordx4 v[166:169], v[138:139], off offset:144
	v_readlane_b32 s48, v237, 1
	v_readlane_b32 s62, v237, 15
	v_readlane_b32 s63, v237, 16
	v_readlane_b32 s56, v237, 9
	v_readlane_b32 s57, v237, 10
	v_lshl_add_u64 v[148:149], s[62:63], 0, v[148:149]
	v_cmp_gt_u32_e32 vcc, 32, v153
	v_readlane_b32 s49, v237, 2
	v_readlane_b32 s50, v237, 3
	v_readlane_b32 s51, v237, 4
	v_readlane_b32 s52, v237, 5
	v_readlane_b32 s53, v237, 6
	v_readlane_b32 s54, v237, 7
	v_readlane_b32 s55, v237, 8
	v_readlane_b32 s58, v237, 11
	v_readlane_b32 s59, v237, 12
	v_readlane_b32 s60, v237, 13
	v_readlane_b32 s61, v237, 14
	s_waitcnt vmcnt(8)
	v_pk_fma_f32 v[128:129], v[112:113], v[212:213], v[220:221]
	v_pk_fma_f32 v[130:131], v[114:115], v[214:215], v[222:223]
	v_pk_fma_f32 v[132:133], v[120:121], v[224:225], v[216:217]
	v_pk_fma_f32 v[134:135], v[122:123], v[226:227], v[218:219]
	global_store_dwordx4 v[148:149], v[128:131], off
	global_store_dwordx4 v[148:149], v[132:135], off offset:16
	global_load_dwordx4 v[212:215], v[142:143], off offset:208
	global_load_dwordx4 v[216:219], v[142:143], off offset:192
	global_load_dwordx4 v[220:223], v[138:139], off offset:192
	global_load_dwordx4 v[224:227], v[138:139], off offset:208
	s_waitcnt vmcnt(10)
	v_pk_fma_f32 v[120:121], v[116:117], v[232:233], v[238:239]
	v_pk_fma_f32 v[124:125], v[124:125], v[228:229], v[242:243]
	v_pk_fma_f32 v[122:123], v[118:119], v[234:235], v[240:241]
	v_pk_fma_f32 v[126:127], v[126:127], v[230:231], v[244:245]
	global_store_dwordx4 v[148:149], v[120:123], off offset:64
	global_store_dwordx4 v[148:149], v[124:127], off offset:80
	global_load_dwordx4 v[228:231], v[142:143], off offset:272
	global_load_dwordx4 v[232:235], v[142:143], off offset:256
	global_load_dwordx4 v[238:241], v[138:139], off offset:256
	global_load_dwordx4 v[242:245], v[138:139], off offset:272
	s_waitcnt vmcnt(12)
	v_pk_fma_f32 v[112:113], v[96:97], v[250:251], v[162:163]
	v_pk_fma_f32 v[114:115], v[98:99], v[252:253], v[164:165]
	v_pk_fma_f32 v[116:117], v[104:105], v[246:247], v[166:167]
	v_pk_fma_f32 v[118:119], v[106:107], v[248:249], v[168:169]
	global_store_dwordx4 v[148:149], v[112:115], off offset:128
	global_store_dwordx4 v[148:149], v[116:119], off offset:144
	global_load_dwordx4 v[246:249], v[142:143], off offset:336
	global_load_dwordx4 v[250:253], v[142:143], off offset:320
	global_load_dwordx4 v[162:165], v[138:139], off offset:320
	global_load_dwordx4 v[166:169], v[138:139], off offset:336
	s_waitcnt vmcnt(12)
	v_pk_fma_f32 v[104:105], v[100:101], v[216:217], v[220:221]
	v_pk_fma_f32 v[108:109], v[108:109], v[212:213], v[224:225]
	v_pk_fma_f32 v[106:107], v[102:103], v[218:219], v[222:223]
	v_pk_fma_f32 v[110:111], v[110:111], v[214:215], v[226:227]
	global_store_dwordx4 v[148:149], v[104:107], off offset:192
	global_store_dwordx4 v[148:149], v[108:111], off offset:208
	global_load_dwordx4 v[212:215], v[142:143], off offset:400
	global_load_dwordx4 v[216:219], v[142:143], off offset:384
	global_load_dwordx4 v[220:223], v[138:139], off offset:384
	global_load_dwordx4 v[224:227], v[138:139], off offset:400
	s_waitcnt vmcnt(12)
	v_pk_fma_f32 v[96:97], v[80:81], v[232:233], v[238:239]
	v_pk_fma_f32 v[98:99], v[82:83], v[234:235], v[240:241]
	v_pk_fma_f32 v[100:101], v[88:89], v[228:229], v[242:243]
	v_pk_fma_f32 v[102:103], v[90:91], v[230:231], v[244:245]
	global_store_dwordx4 v[148:149], v[96:99], off offset:256
	global_store_dwordx4 v[148:149], v[100:103], off offset:272
	global_load_dwordx4 v[228:231], v[142:143], off offset:464
	global_load_dwordx4 v[232:235], v[142:143], off offset:448
	global_load_dwordx4 v[238:241], v[138:139], off offset:448
	global_load_dwordx4 v[242:245], v[138:139], off offset:464
	s_waitcnt vmcnt(12)
	v_pk_fma_f32 v[88:89], v[84:85], v[250:251], v[162:163]
	v_pk_fma_f32 v[92:93], v[92:93], v[246:247], v[166:167]
	v_pk_fma_f32 v[90:91], v[86:87], v[252:253], v[164:165]
	v_pk_fma_f32 v[94:95], v[94:95], v[248:249], v[168:169]
	global_store_dwordx4 v[148:149], v[88:91], off offset:320
	global_store_dwordx4 v[148:149], v[92:95], off offset:336
	s_waitcnt vmcnt(8)
	v_pk_fma_f32 v[80:81], v[64:65], v[216:217], v[220:221]
	v_pk_fma_f32 v[82:83], v[66:67], v[218:219], v[222:223]
	v_pk_fma_f32 v[84:85], v[72:73], v[212:213], v[224:225]
	v_pk_fma_f32 v[86:87], v[74:75], v[214:215], v[226:227]
	global_store_dwordx4 v[148:149], v[80:83], off offset:384
	global_store_dwordx4 v[148:149], v[84:87], off offset:400
	s_waitcnt vmcnt(4)
	v_pk_fma_f32 v[72:73], v[68:69], v[232:233], v[238:239]
	v_pk_fma_f32 v[76:77], v[76:77], v[228:229], v[242:243]
	v_pk_fma_f32 v[74:75], v[70:71], v[234:235], v[240:241]
	v_pk_fma_f32 v[78:79], v[78:79], v[230:231], v[244:245]
	global_store_dwordx4 v[148:149], v[72:75], off offset:448
	global_store_dwordx4 v[148:149], v[76:79], off offset:464
	v_or_b32_e32 v138, 32, v140
	v_ashrrev_i32_e32 v139, 31, v138
	v_lshlrev_b64 v[64:65], 10, v[138:139]
	v_lshl_add_u64 v[64:65], v[64:65], 0, v[136:137]
	v_lshlrev_b64 v[148:149], 2, v[64:65]
	v_lshl_add_u64 v[170:171], s[36:37], 0, v[148:149]
	global_load_dwordx4 v[246:249], v[170:171], off offset:16
	global_load_dwordx4 v[250:253], v[170:171], off
	global_load_dwordx4 v[162:165], v[146:147], off
	global_load_dwordx4 v[166:169], v[142:143], off offset:16
	global_load_dwordx4 v[212:215], v[142:143], off offset:80
	global_load_dwordx4 v[216:219], v[142:143], off offset:64
	global_load_dwordx4 v[220:223], v[170:171], off offset:64
	global_load_dwordx4 v[224:227], v[170:171], off offset:80
	global_load_dwordx4 v[228:231], v[142:143], off offset:144
	global_load_dwordx4 v[232:235], v[142:143], off offset:128
	global_load_dwordx4 v[238:241], v[170:171], off offset:128
	global_load_dwordx4 v[242:245], v[170:171], off offset:144
	v_lshl_add_u64 v[146:147], s[62:63], 0, v[148:149]
	s_waitcnt vmcnt(8)
	v_pk_fma_f32 v[64:65], v[48:49], v[162:163], v[250:251]
	v_pk_fma_f32 v[66:67], v[50:51], v[164:165], v[252:253]
	v_pk_fma_f32 v[68:69], v[56:57], v[166:167], v[246:247]
	v_pk_fma_f32 v[70:71], v[58:59], v[168:169], v[248:249]
	global_store_dwordx4 v[146:147], v[64:67], off
	global_store_dwordx4 v[146:147], v[68:71], off offset:16
	global_load_dwordx4 v[246:249], v[142:143], off offset:208
	global_load_dwordx4 v[250:253], v[142:143], off offset:192
	global_load_dwordx4 v[162:165], v[170:171], off offset:192
	global_load_dwordx4 v[166:169], v[170:171], off offset:208
	s_waitcnt vmcnt(10)
	v_pk_fma_f32 v[56:57], v[52:53], v[216:217], v[220:221]
	v_pk_fma_f32 v[60:61], v[60:61], v[212:213], v[224:225]
	v_pk_fma_f32 v[58:59], v[54:55], v[218:219], v[222:223]
	v_pk_fma_f32 v[62:63], v[62:63], v[214:215], v[226:227]
	global_store_dwordx4 v[146:147], v[56:59], off offset:64
	global_store_dwordx4 v[146:147], v[60:63], off offset:80
	global_load_dwordx4 v[212:215], v[142:143], off offset:272
	global_load_dwordx4 v[216:219], v[142:143], off offset:256
	global_load_dwordx4 v[220:223], v[170:171], off offset:256
	global_load_dwordx4 v[224:227], v[170:171], off offset:272
	s_waitcnt vmcnt(12)
	v_pk_fma_f32 v[48:49], v[32:33], v[232:233], v[238:239]
	v_pk_fma_f32 v[50:51], v[34:35], v[234:235], v[240:241]
	v_pk_fma_f32 v[52:53], v[40:41], v[228:229], v[242:243]
	v_pk_fma_f32 v[54:55], v[42:43], v[230:231], v[244:245]
	global_store_dwordx4 v[146:147], v[48:51], off offset:128
	global_store_dwordx4 v[146:147], v[52:55], off offset:144
	global_load_dwordx4 v[228:231], v[142:143], off offset:336
	global_load_dwordx4 v[232:235], v[142:143], off offset:320
	global_load_dwordx4 v[238:241], v[170:171], off offset:320
	global_load_dwordx4 v[242:245], v[170:171], off offset:336
	s_waitcnt vmcnt(12)
	v_pk_fma_f32 v[40:41], v[36:37], v[250:251], v[162:163]
	v_pk_fma_f32 v[44:45], v[44:45], v[246:247], v[166:167]
	v_pk_fma_f32 v[42:43], v[38:39], v[252:253], v[164:165]
	v_pk_fma_f32 v[46:47], v[46:47], v[248:249], v[168:169]
	global_store_dwordx4 v[146:147], v[40:43], off offset:192
	global_store_dwordx4 v[146:147], v[44:47], off offset:208
	global_load_dwordx4 v[246:249], v[142:143], off offset:400
	global_load_dwordx4 v[250:253], v[142:143], off offset:384
	global_load_dwordx4 v[162:165], v[170:171], off offset:384
	global_load_dwordx4 v[166:169], v[170:171], off offset:400
	s_waitcnt vmcnt(12)
	v_pk_fma_f32 v[32:33], v[16:17], v[216:217], v[220:221]
	v_pk_fma_f32 v[34:35], v[18:19], v[218:219], v[222:223]
	v_pk_fma_f32 v[36:37], v[24:25], v[212:213], v[224:225]
	v_pk_fma_f32 v[38:39], v[26:27], v[214:215], v[226:227]
	global_store_dwordx4 v[146:147], v[32:35], off offset:256
	global_store_dwordx4 v[146:147], v[36:39], off offset:272
	global_load_dwordx4 v[212:215], v[142:143], off offset:464
	global_load_dwordx4 v[216:219], v[142:143], off offset:448
	global_load_dwordx4 v[220:223], v[170:171], off offset:448
	global_load_dwordx4 v[224:227], v[170:171], off offset:464
	s_waitcnt vmcnt(12)
	v_pk_fma_f32 v[20:21], v[20:21], v[232:233], v[238:239]
	v_pk_fma_f32 v[24:25], v[28:29], v[228:229], v[242:243]
	v_pk_fma_f32 v[22:23], v[22:23], v[234:235], v[240:241]
	v_pk_fma_f32 v[26:27], v[30:31], v[230:231], v[244:245]
	global_store_dwordx4 v[146:147], v[20:23], off offset:320
	global_store_dwordx4 v[146:147], v[24:27], off offset:336
	s_waitcnt vmcnt(8)
	v_pk_fma_f32 v[16:17], v[0:1], v[250:251], v[162:163]
	v_pk_fma_f32 v[18:19], v[2:3], v[252:253], v[164:165]
	v_pk_fma_f32 v[8:9], v[8:9], v[246:247], v[166:167]
	v_pk_fma_f32 v[10:11], v[10:11], v[248:249], v[168:169]
	global_store_dwordx4 v[146:147], v[16:19], off offset:384
	global_store_dwordx4 v[146:147], v[8:11], off offset:400
	s_waitcnt vmcnt(4)
	v_pk_fma_f32 v[0:1], v[4:5], v[216:217], v[220:221]
	v_pk_fma_f32 v[4:5], v[12:13], v[212:213], v[224:225]
	v_pk_fma_f32 v[2:3], v[6:7], v[218:219], v[222:223]
	v_pk_fma_f32 v[6:7], v[14:15], v[214:215], v[226:227]
	global_store_dwordx4 v[146:147], v[0:3], off offset:448
	global_store_dwordx4 v[146:147], v[4:7], off offset:464
	v_pk_mul_f32 v[12:13], v[128:129], v[128:129]
	v_pk_mul_f32 v[14:15], v[130:131], v[130:131]
	v_add_f32_e32 v12, v12, v13
	v_add_f32_e32 v12, v14, v12
	v_pk_mul_f32 v[28:29], v[120:121], v[120:121]
	v_add_f32_e32 v12, v15, v12
	v_add_f32_e32 v12, v12, v28
	v_pk_mul_f32 v[30:31], v[122:123], v[122:123]
	v_add_f32_e32 v12, v29, v12
	v_add_f32_e32 v12, v30, v12
	v_pk_mul_f32 v[142:143], v[132:133], v[132:133]
	v_add_f32_e32 v12, v31, v12
	v_add_f32_e32 v12, v142, v12
	v_pk_mul_f32 v[146:147], v[134:135], v[134:135]
	v_add_f32_e32 v12, v143, v12
	v_add_f32_e32 v12, v146, v12
	v_pk_mul_f32 v[148:149], v[124:125], v[124:125]
	v_add_f32_e32 v12, v147, v12
	v_add_f32_e32 v12, v148, v12
	v_pk_mul_f32 v[162:163], v[126:127], v[126:127]
	v_add_f32_e32 v12, v149, v12
	v_add_f32_e32 v12, v162, v12
	v_pk_mul_f32 v[164:165], v[112:113], v[112:113]
	v_add_f32_e32 v12, v163, v12
	v_add_f32_e32 v12, v164, v12
	v_pk_mul_f32 v[166:167], v[114:115], v[114:115]
	v_add_f32_e32 v12, v165, v12
	v_add_f32_e32 v12, v166, v12
	v_pk_mul_f32 v[168:169], v[104:105], v[104:105]
	v_add_f32_e32 v12, v167, v12
	v_add_f32_e32 v12, v168, v12
	v_pk_mul_f32 v[170:171], v[106:107], v[106:107]
	v_add_f32_e32 v12, v169, v12
	v_add_f32_e32 v12, v170, v12
	v_pk_mul_f32 v[172:173], v[116:117], v[116:117]
	v_add_f32_e32 v12, v171, v12
	v_add_f32_e32 v12, v172, v12
	v_pk_mul_f32 v[174:175], v[118:119], v[118:119]
	v_add_f32_e32 v12, v173, v12
	v_add_f32_e32 v12, v174, v12
	v_pk_mul_f32 v[176:177], v[108:109], v[108:109]
	v_add_f32_e32 v12, v175, v12
	v_add_f32_e32 v12, v176, v12
	v_pk_mul_f32 v[178:179], v[110:111], v[110:111]
	v_add_f32_e32 v12, v177, v12
	v_add_f32_e32 v12, v178, v12
	v_pk_mul_f32 v[180:181], v[96:97], v[96:97]
	v_add_f32_e32 v12, v179, v12
	v_add_f32_e32 v12, v180, v12
	v_pk_mul_f32 v[182:183], v[98:99], v[98:99]
	v_add_f32_e32 v12, v181, v12
	v_add_f32_e32 v12, v182, v12
	v_pk_mul_f32 v[184:185], v[88:89], v[88:89]
	v_add_f32_e32 v12, v183, v12
	v_add_f32_e32 v12, v184, v12
	v_pk_mul_f32 v[186:187], v[90:91], v[90:91]
	v_add_f32_e32 v12, v185, v12
	v_add_f32_e32 v12, v186, v12
	v_pk_mul_f32 v[188:189], v[100:101], v[100:101]
	v_add_f32_e32 v12, v187, v12
	v_add_f32_e32 v12, v188, v12
	v_pk_mul_f32 v[190:191], v[102:103], v[102:103]
	v_add_f32_e32 v12, v189, v12
	v_add_f32_e32 v12, v190, v12
	v_pk_mul_f32 v[192:193], v[92:93], v[92:93]
	v_add_f32_e32 v12, v191, v12
	v_add_f32_e32 v12, v192, v12
	v_pk_mul_f32 v[194:195], v[94:95], v[94:95]
	v_add_f32_e32 v12, v193, v12
	v_add_f32_e32 v12, v194, v12
	v_pk_mul_f32 v[196:197], v[80:81], v[80:81]
	v_add_f32_e32 v12, v195, v12
	v_add_f32_e32 v12, v196, v12
	v_pk_mul_f32 v[198:199], v[82:83], v[82:83]
	v_add_f32_e32 v12, v197, v12
	v_add_f32_e32 v12, v198, v12
	v_pk_mul_f32 v[200:201], v[72:73], v[72:73]
	v_add_f32_e32 v12, v199, v12
	v_add_f32_e32 v12, v200, v12
	v_pk_mul_f32 v[202:203], v[74:75], v[74:75]
	v_add_f32_e32 v12, v201, v12
	v_add_f32_e32 v12, v202, v12
	v_pk_mul_f32 v[204:205], v[84:85], v[84:85]
	v_add_f32_e32 v12, v203, v12
	v_add_f32_e32 v12, v204, v12
	v_pk_mul_f32 v[206:207], v[86:87], v[86:87]
	v_add_f32_e32 v12, v205, v12
	v_add_f32_e32 v12, v206, v12
	v_pk_mul_f32 v[208:209], v[76:77], v[76:77]
	v_add_f32_e32 v12, v207, v12
	v_add_f32_e32 v12, v208, v12
	v_pk_mul_f32 v[210:211], v[78:79], v[78:79]
	v_add_f32_e32 v12, v209, v12
	v_add_f32_e32 v12, v210, v12
	v_add_f32_e32 v14, v211, v12
	ds_bpermute_b32 v15, v145, v14
	s_lshl_b64 s[56:57], s[82:83], 2
	s_add_u32 s56, s0, s56
	s_addc_u32 s57, s1, s57
	v_lshlrev_b32_e32 v12, 2, v152
	v_mov_b32_e32 v13, v137
	v_lshl_add_u64 v[12:13], s[56:57], 0, v[12:13]
	s_and_saveexec_b64 s[56:57], vcc
	s_cbranch_execz .LBB0_392
	s_waitcnt lgkmcnt(0)
	v_add_f32_e32 v14, v14, v15
	global_atomic_add_f32 v[12:13], v14, off

.LBB0_808:
	s_waitcnt vmcnt(0)
	s_waitcnt lgkmcnt(0)
	s_barrier
	s_add_i32 s8, 0, 0x10000
	v_add_u32_e32 v192, s8, v168
	ds_read_b128 v[80:83], v192
	ds_read_b128 v[84:87], v192 offset:8192
	v_add_u32_e32 v193, s8, v170
	ds_read_b128 v[194:197], v193
	ds_read_b128 v[198:201], v193 offset:8192
	s_add_i32 s19, 0, 0x16000
	s_waitcnt lgkmcnt(0)
	v_mfma_f32_32x32x16_bf16 v[96:111], v[80:83], v[140:143], 0
	v_exp_f32_e32 v226, v76
	v_exp_f32_e32 v227, v77
	v_exp_f32_e32 v228, v78
	v_exp_f32_e32 v79, v79
	v_cvt_pk_bf16_f32 v78, v226, v227
	s_waitcnt lgkmcnt(2)
	v_mfma_f32_32x32x16_bf16 v[80:95], v[84:87], v[140:143], 0
	s_waitcnt lgkmcnt(1)
	v_mfma_f32_32x32x16_bf16 v[96:111], v[194:197], v[136:139], v[96:111]
	v_add_u32_e32 v194, s8, v172
	v_add_u32_e32 v195, s8, v174
	s_waitcnt lgkmcnt(0)
	v_mfma_f32_32x32x16_bf16 v[80:95], v[198:201], v[136:139], v[80:95]
	ds_read_b128 v[196:199], v194
	ds_read_b128 v[200:203], v194 offset:8192
	s_waitcnt lgkmcnt(0)
	v_mfma_f32_32x32x16_bf16 v[96:111], v[196:199], v[132:135], v[96:111]
	s_waitcnt lgkmcnt(0)
	v_mfma_f32_32x32x16_bf16 v[80:95], v[200:203], v[132:135], v[80:95]
	ds_read_b128 v[196:199], v195
	ds_read_b128 v[200:203], v195 offset:8192
	s_waitcnt lgkmcnt(0)
	v_mfma_f32_32x32x16_bf16 v[96:111], v[196:199], v[128:131], v[96:111]
	v_add_u32_e32 v196, s8, v176
	v_add_u32_e32 v197, s8, v178
	s_waitcnt lgkmcnt(0)
	v_mfma_f32_32x32x16_bf16 v[80:95], v[200:203], v[128:131], v[80:95]
	ds_read_b128 v[198:201], v196
	ds_read_b128 v[214:217], v196 offset:8192
	s_waitcnt lgkmcnt(0)
	v_mfma_f32_32x32x16_bf16 v[96:111], v[198:201], v[124:127], v[96:111]
	s_waitcnt lgkmcnt(0)
	v_mfma_f32_32x32x16_bf16 v[80:95], v[214:217], v[124:127], v[80:95]
	ds_read_b128 v[198:201], v197
	ds_read_b128 v[214:217], v197 offset:8192
	s_waitcnt lgkmcnt(0)
	v_mfma_f32_32x32x16_bf16 v[96:111], v[198:201], v[120:123], v[96:111]
	v_add_u32_e32 v198, s8, v180
	v_add_u32_e32 v199, s8, v182
	s_waitcnt lgkmcnt(0)
	v_mfma_f32_32x32x16_bf16 v[80:95], v[214:217], v[120:123], v[80:95]
	ds_read_b128 v[200:203], v198
	ds_read_b128 v[214:217], v198 offset:8192
	s_waitcnt lgkmcnt(0)
	v_mfma_f32_32x32x16_bf16 v[96:111], v[200:203], v[116:119], v[96:111]
	s_waitcnt lgkmcnt(0)
	v_mfma_f32_32x32x16_bf16 v[80:95], v[214:217], v[116:119], v[80:95]
	ds_read_b128 v[200:203], v199
	ds_read_b128 v[214:217], v199 offset:8192
	s_waitcnt lgkmcnt(0)
	v_mfma_f32_32x32x16_bf16 v[96:111], v[200:203], v[112:115], v[96:111]
	v_add_u32_e32 v200, s19, v184
	v_add_u32_e32 v201, s19, v186
	v_add_u32_e32 v202, s19, v188
	v_add_u32_e32 v203, s19, v190
	s_waitcnt lgkmcnt(0)
	v_mfma_f32_32x32x16_bf16 v[80:95], v[214:217], v[112:115], v[80:95]
	ds_read_b128 v[214:217], v167
	ds_read_b128 v[218:221], v200
	ds_read_b128 v[222:225], v200 offset:4096
	s_waitcnt lgkmcnt(0)
	v_mfma_f32_32x32x16_bf16 v[96:111], v[218:221], v[214:217], v[96:111]
	s_waitcnt lgkmcnt(0)
	v_mfma_f32_32x32x16_bf16 v[80:95], v[222:225], v[214:217], v[80:95]
	ds_read_b128 v[214:217], v167 offset:8192
	ds_read_b128 v[218:221], v201
	ds_read_b128 v[222:225], v201 offset:4096
	s_waitcnt lgkmcnt(0)
	v_mfma_f32_32x32x16_bf16 v[96:111], v[218:221], v[214:217], v[96:111]
	s_waitcnt lgkmcnt(0)
	v_mfma_f32_32x32x16_bf16 v[80:95], v[222:225], v[214:217], v[80:95]
	ds_read_b128 v[214:217], v167 offset:16384
	ds_read_b128 v[218:221], v202
	ds_read_b128 v[222:225], v202 offset:4096
	s_waitcnt lgkmcnt(0)
	v_mfma_f32_32x32x16_bf16 v[96:111], v[218:221], v[214:217], v[96:111]
	s_waitcnt lgkmcnt(0)
	v_mfma_f32_32x32x16_bf16 v[80:95], v[222:225], v[214:217], v[80:95]
	ds_read_b128 v[214:217], v167 offset:24576
	ds_read_b128 v[218:221], v203
	ds_read_b128 v[222:225], v203 offset:4096
	s_waitcnt lgkmcnt(0)
	v_mfma_f32_32x32x16_bf16 v[96:111], v[218:221], v[214:217], v[96:111]
	v_exp_f32_e32 v218, v68
	v_exp_f32_e32 v219, v69
	v_exp_f32_e32 v220, v70
	v_exp_f32_e32 v221, v71
	v_cvt_pk_bf16_f32 v68, v211, v213
	v_cvt_pk_bf16_f32 v69, v209, v212
	v_cvt_pk_bf16_f32 v70, v208, v210
	s_waitcnt lgkmcnt(0)
	v_mfma_f32_32x32x16_bf16 v[80:95], v[222:225], v[214:217], v[80:95]
	v_exp_f32_e32 v214, v64
	v_add_f32_e32 v64, 0, v211
	v_add_f32_e32 v64, v213, v64
	v_add_f32_e32 v64, v209, v64
	v_add_f32_e32 v64, v212, v64
	v_add_f32_e32 v64, v208, v64
	v_add_f32_e32 v64, v210, v64
	v_add_f32_e32 v64, v206, v64
	v_add_f32_e32 v64, v207, v64
	v_add_f32_e32 v64, v161, v64
	v_add_f32_e32 v64, v205, v64
	v_add_f32_e32 v64, v160, v64
	v_add_f32_e32 v64, v204, v64
	v_add_f32_e32 v64, v157, v64
	v_exp_f32_e32 v215, v65
	v_add_f32_e32 v64, v159, v64
	v_exp_f32_e32 v216, v66
	v_add_f32_e32 v64, v156, v64
	v_exp_f32_e32 v217, v67
	v_add_f32_e32 v64, v158, v64
	v_add_f32_e32 v64, v214, v64
	v_add_f32_e32 v64, v215, v64
	v_add_f32_e32 v64, v216, v64
	v_add_f32_e32 v64, v217, v64
	v_exp_f32_e32 v222, v72
	v_add_f32_e32 v64, v218, v64
	v_exp_f32_e32 v223, v73
	v_add_f32_e32 v64, v219, v64
	v_exp_f32_e32 v224, v74
	v_add_f32_e32 v64, v220, v64
	v_exp_f32_e32 v225, v75
	v_add_f32_e32 v64, v221, v64
	v_add_f32_e32 v64, v222, v64
	v_add_f32_e32 v64, v223, v64
	v_add_f32_e32 v64, v224, v64
	v_add_f32_e32 v64, v225, v64
	v_add_f32_e32 v64, v226, v64
	v_add_f32_e32 v64, v227, v64
	v_add_f32_e32 v64, v228, v64
	v_add_f32_e32 v64, v79, v64
	v_mov_b32_e32 v65, v64
	s_nop 1
	v_permlane32_swap_b32_e32 v64, v65
	v_add_f32_e32 v64, v64, v65
	v_add_f32_e32 v146, v146, v64
	v_cvt_pk_bf16_f32 v71, v206, v207
	v_cvt_pk_bf16_f32 v64, v161, v205
	v_cvt_pk_bf16_f32 v65, v160, v204
	v_cvt_pk_bf16_f32 v66, v157, v159
	v_cvt_pk_bf16_f32 v67, v156, v158
	v_cvt_pk_bf16_f32 v72, v214, v215
	v_cvt_pk_bf16_f32 v73, v216, v217
	v_cvt_pk_bf16_f32 v74, v218, v219
	v_cvt_pk_bf16_f32 v75, v220, v221
	v_cvt_pk_bf16_f32 v76, v222, v223
	v_cvt_pk_bf16_f32 v77, v224, v225
	v_cvt_pk_bf16_f32 v79, v228, v79
	s_cmp_gt_i32 s18, 0
	s_cselect_b32 s20, -1, 2
	s_mov_b32 m0, s6
	s_add_i32 s20, s20, s18
	s_add_u32 s98, s28, s64
	s_addc_u32 s99, s29, s65
	global_load_lds_dwordx4 v154, s[98:99]
	s_mov_b32 m0, s7
	s_lshl_b32 s20, s20, 14
	s_add_u32 s98, s28, s66
	s_addc_u32 s99, s29, s67
	global_load_lds_dwordx4 v154, s[98:99]
	s_add_i32 s20, s5, s20
	s_mov_b32 m0, s20
	s_nop 0
	s_add_u32 s98, s28, s68
	s_addc_u32 s99, s29, s69
	global_load_lds_dwordx4 v152, s[98:99]
	s_add_i32 m0, s20, 0x2000
	s_nop 0
	s_add_u32 s98, s28, s70
	s_addc_u32 s99, s29, s71
	global_load_lds_dwordx4 v152, s[98:99]
	s_add_i32 m0, s14, s1
	s_nop 0
	s_add_u32 s98, s28, s72
	s_addc_u32 s99, s29, s73
	global_load_lds_dwordx4 v150, s[98:99]
	v_lshl_add_u32 v224, s18, 14, v166
	ds_read_b64_tr_b16 v[204:205], v224 offset:0
	ds_read_b64_tr_b16 v[206:207], v224 offset:0x800
	ds_read_b64_tr_b16 v[208:209], v224 offset:0x1000
	ds_read_b64_tr_b16 v[210:211], v224 offset:0x1800
	ds_read_b64_tr_b16 v[212:213], v224 offset:0x2000
	ds_read_b64_tr_b16 v[214:215], v224 offset:0x2800
	ds_read_b64_tr_b16 v[216:217], v224 offset:0x3000
	ds_read_b64_tr_b16 v[218:219], v224 offset:0x3800
	s_add_i32 s20, s18, 1
	s_waitcnt lgkmcnt(0)
	s_cmp_lg_u32 s18, 2
	v_mfma_f32_32x32x16_bf16 v[48:63], v[68:71], v[204:207], v[48:63]
	ds_read_b64_tr_b16 v[204:205], v224 offset:0x200
	ds_read_b64_tr_b16 v[206:207], v224 offset:0xa00
	s_cselect_b32 s18, s20, 0
	v_exp_f32_e32 v225, v101
	v_exp_f32_e32 v226, v102
	v_exp_f32_e32 v227, v103
	v_exp_f32_e32 v228, v104
	v_mfma_f32_32x32x16_bf16 v[48:63], v[64:67], v[208:211], v[48:63]
	ds_read_b64_tr_b16 v[208:209], v224 offset:0x1200
	ds_read_b64_tr_b16 v[210:211], v224 offset:0x1a00
	v_exp_f32_e32 v229, v105
	v_exp_f32_e32 v230, v106
	v_exp_f32_e32 v231, v107
	v_exp_f32_e32 v232, v108
	v_exp_f32_e32 v233, v109
	v_mfma_f32_32x32x16_bf16 v[48:63], v[72:75], v[212:215], v[48:63]
	ds_read_b64_tr_b16 v[212:213], v224 offset:0x2200
	ds_read_b64_tr_b16 v[214:215], v224 offset:0x2a00
	ds_read_b64_tr_b16 v[220:221], v224 offset:0x3200
	ds_read_b64_tr_b16 v[222:223], v224 offset:0x3a00
	v_exp_f32_e32 v234, v110
	s_waitcnt lgkmcnt(0)
	v_exp_f32_e32 v235, v111
	v_mfma_f32_32x32x16_bf16 v[32:47], v[68:71], v[204:207], v[32:47]
	ds_read_b64_tr_b16 v[204:205], v224 offset:0x400
	ds_read_b64_tr_b16 v[206:207], v224 offset:0xc00
	v_mfma_f32_32x32x16_bf16 v[32:47], v[64:67], v[208:211], v[32:47]
	ds_read_b64_tr_b16 v[208:209], v224 offset:0x1400
	ds_read_b64_tr_b16 v[210:211], v224 offset:0x1c00
	v_mfma_f32_32x32x16_bf16 v[48:63], v[76:79], v[216:219], v[48:63]
	v_mfma_f32_32x32x16_bf16 v[32:47], v[72:75], v[212:215], v[32:47]
	ds_read_b64_tr_b16 v[212:213], v224 offset:0x2400
	ds_read_b64_tr_b16 v[214:215], v224 offset:0x2c00
	ds_read_b64_tr_b16 v[216:217], v224 offset:0x3400
	ds_read_b64_tr_b16 v[218:219], v224 offset:0x3c00
	s_nop 0
	s_waitcnt lgkmcnt(0)
	s_nop 0
	v_mfma_f32_32x32x16_bf16 v[16:31], v[68:71], v[204:207], v[16:31]
	ds_read_b64_tr_b16 v[204:205], v224 offset:0x600
	ds_read_b64_tr_b16 v[206:207], v224 offset:0xe00
	v_mfma_f32_32x32x16_bf16 v[16:31], v[64:67], v[208:211], v[16:31]
	ds_read_b64_tr_b16 v[208:209], v224 offset:0x1600
	ds_read_b64_tr_b16 v[210:211], v224 offset:0x1e00
	v_mfma_f32_32x32x16_bf16 v[16:31], v[72:75], v[212:215], v[16:31]
	ds_read_b64_tr_b16 v[212:213], v224 offset:0x2600
	ds_read_b64_tr_b16 v[214:215], v224 offset:0x2e00
	v_mfma_f32_32x32x16_bf16 v[16:31], v[76:79], v[216:219], v[16:31]
	ds_read_b64_tr_b16 v[216:217], v224 offset:0x3600
	ds_read_b64_tr_b16 v[218:219], v224 offset:0x3e00
	v_exp_f32_e32 v224, v100
	s_waitcnt lgkmcnt(0)
	s_waitcnt vmcnt(0)
	s_waitcnt lgkmcnt(0)
	s_barrier
	v_mfma_f32_32x32x16_bf16 v[0:15], v[68:71], v[204:207], v[0:15]
	v_mfma_f32_32x32x16_bf16 v[0:15], v[64:67], v[208:211], v[0:15]
	v_mfma_f32_32x32x16_bf16 v[0:15], v[72:75], v[212:215], v[0:15]
	v_mfma_f32_32x32x16_bf16 v[32:47], v[76:79], v[220:223], v[32:47]
	v_exp_f32_e32 v220, v96
	v_exp_f32_e32 v221, v97
	v_exp_f32_e32 v222, v98
	v_exp_f32_e32 v223, v99
	v_mfma_f32_32x32x16_bf16 v[0:15], v[76:79], v[216:219], v[0:15]
	ds_read_b128 v[64:67], v169 offset:49152
	ds_read_b128 v[68:71], v169 offset:57344
	ds_read_b128 v[204:207], v171 offset:49152
	ds_read_b128 v[208:211], v171 offset:57344
	v_exp_f32_e32 v80, v80
	v_exp_f32_e32 v81, v81
	s_waitcnt lgkmcnt(0)
	v_mfma_f32_32x32x16_bf16 v[96:111], v[64:67], v[140:143], 0
	v_exp_f32_e32 v82, v82
	v_exp_f32_e32 v83, v83
	v_mfma_f32_32x32x16_bf16 v[64:79], v[68:71], v[140:143], 0
	v_mfma_f32_32x32x16_bf16 v[96:111], v[204:207], v[136:139], v[96:111]
	v_mfma_f32_32x32x16_bf16 v[64:79], v[208:211], v[136:139], v[64:79]
	ds_read_b128 v[204:207], v173 offset:49152
	ds_read_b128 v[208:211], v173 offset:57344
	s_waitcnt lgkmcnt(0)
	v_mfma_f32_32x32x16_bf16 v[96:111], v[204:207], v[132:135], v[96:111]
	v_mfma_f32_32x32x16_bf16 v[64:79], v[208:211], v[132:135], v[64:79]
	ds_read_b128 v[204:207], v175 offset:49152
	ds_read_b128 v[208:211], v175 offset:57344
	s_waitcnt lgkmcnt(0)
	v_mfma_f32_32x32x16_bf16 v[96:111], v[204:207], v[128:131], v[96:111]
	v_mfma_f32_32x32x16_bf16 v[64:79], v[208:211], v[128:131], v[64:79]
	ds_read_b128 v[204:207], v177 offset:49152
	ds_read_b128 v[208:211], v177 offset:57344
	s_waitcnt lgkmcnt(0)
	v_mfma_f32_32x32x16_bf16 v[96:111], v[204:207], v[124:127], v[96:111]
	v_mfma_f32_32x32x16_bf16 v[64:79], v[208:211], v[124:127], v[64:79]
	ds_read_b128 v[204:207], v179 offset:49152
	ds_read_b128 v[208:211], v179 offset:57344
	s_waitcnt lgkmcnt(0)
	v_mfma_f32_32x32x16_bf16 v[96:111], v[204:207], v[120:123], v[96:111]
	v_mfma_f32_32x32x16_bf16 v[64:79], v[208:211], v[120:123], v[64:79]
	ds_read_b128 v[204:207], v181 offset:49152
	ds_read_b128 v[208:211], v181 offset:57344
	s_waitcnt lgkmcnt(0)
	v_mfma_f32_32x32x16_bf16 v[96:111], v[204:207], v[116:119], v[96:111]
	v_mfma_f32_32x32x16_bf16 v[64:79], v[208:211], v[116:119], v[64:79]
	ds_read_b128 v[204:207], v183 offset:49152
	ds_read_b128 v[208:211], v183 offset:57344
	s_waitcnt lgkmcnt(0)
	v_mfma_f32_32x32x16_bf16 v[96:111], v[204:207], v[112:115], v[96:111]
	v_mfma_f32_32x32x16_bf16 v[64:79], v[208:211], v[112:115], v[64:79]
	ds_read_b128 v[204:207], v167
	ds_read_b128 v[208:211], v185
	ds_read_b128 v[212:215], v185 offset:4096
	s_waitcnt lgkmcnt(0)
	v_mfma_f32_32x32x16_bf16 v[96:111], v[208:211], v[204:207], v[96:111]
	v_mfma_f32_32x32x16_bf16 v[64:79], v[212:215], v[204:207], v[64:79]
	ds_read_b128 v[204:207], v167 offset:8192
	ds_read_b128 v[208:211], v187
	ds_read_b128 v[212:215], v187 offset:4096
	s_waitcnt lgkmcnt(0)
	v_mfma_f32_32x32x16_bf16 v[96:111], v[208:211], v[204:207], v[96:111]
	v_mfma_f32_32x32x16_bf16 v[64:79], v[212:215], v[204:207], v[64:79]
	ds_read_b128 v[204:207], v167 offset:16384
	ds_read_b128 v[208:211], v189
	ds_read_b128 v[212:215], v189 offset:4096
	s_waitcnt lgkmcnt(0)
	v_mfma_f32_32x32x16_bf16 v[96:111], v[208:211], v[204:207], v[96:111]
	v_mfma_f32_32x32x16_bf16 v[64:79], v[212:215], v[204:207], v[64:79]
	ds_read_b128 v[204:207], v167 offset:24576
	ds_read_b128 v[208:211], v191
	ds_read_b128 v[212:215], v191 offset:4096
	s_waitcnt lgkmcnt(0)
	v_mfma_f32_32x32x16_bf16 v[96:111], v[208:211], v[204:207], v[96:111]
	v_exp_f32_e32 v208, v88
	v_exp_f32_e32 v209, v89
	v_exp_f32_e32 v210, v90
	v_exp_f32_e32 v211, v91
	v_cvt_pk_bf16_f32 v88, v228, v229
	v_cvt_pk_bf16_f32 v89, v230, v231
	v_cvt_pk_bf16_f32 v90, v232, v233
	v_mfma_f32_32x32x16_bf16 v[64:79], v[212:215], v[204:207], v[64:79]
	v_exp_f32_e32 v204, v84
	v_add_f32_e32 v84, 0, v220
	v_add_f32_e32 v84, v221, v84
	v_add_f32_e32 v84, v222, v84
	v_add_f32_e32 v84, v223, v84
	v_add_f32_e32 v84, v224, v84
	v_add_f32_e32 v84, v225, v84
	v_add_f32_e32 v84, v226, v84
	v_add_f32_e32 v84, v227, v84
	v_add_f32_e32 v84, v228, v84
	v_add_f32_e32 v84, v229, v84
	v_add_f32_e32 v84, v230, v84
	v_add_f32_e32 v84, v231, v84
	v_add_f32_e32 v84, v232, v84
	v_add_f32_e32 v84, v233, v84
	v_add_f32_e32 v84, v234, v84
	v_add_f32_e32 v84, v235, v84
	v_add_f32_e32 v84, v80, v84
	v_exp_f32_e32 v205, v85
	v_add_f32_e32 v84, v81, v84
	v_exp_f32_e32 v206, v86
	v_add_f32_e32 v84, v82, v84
	v_exp_f32_e32 v207, v87
	v_add_f32_e32 v84, v83, v84
	v_add_f32_e32 v84, v204, v84
	v_add_f32_e32 v84, v205, v84
	v_add_f32_e32 v84, v206, v84
	v_add_f32_e32 v84, v207, v84
	v_exp_f32_e32 v212, v92
	v_add_f32_e32 v84, v208, v84
	v_exp_f32_e32 v213, v93
	v_add_f32_e32 v84, v209, v84
	v_exp_f32_e32 v214, v94
	v_add_f32_e32 v84, v210, v84
	v_exp_f32_e32 v215, v95
	v_add_f32_e32 v84, v211, v84
	v_add_f32_e32 v84, v212, v84
	v_add_f32_e32 v84, v213, v84
	v_add_f32_e32 v84, v214, v84
	v_add_f32_e32 v84, v215, v84
	v_mov_b32_e32 v85, v84
	s_nop 1
	v_permlane32_swap_b32_e32 v84, v85
	v_add_f32_e32 v84, v84, v85
	v_add_f32_e32 v146, v146, v84
	v_cvt_pk_bf16_f32 v84, v220, v221
	v_cvt_pk_bf16_f32 v85, v222, v223
	v_cvt_pk_bf16_f32 v86, v224, v225
	v_cvt_pk_bf16_f32 v87, v226, v227
	v_cvt_pk_bf16_f32 v91, v234, v235
	v_cvt_pk_bf16_f32 v92, v80, v81
	v_cvt_pk_bf16_f32 v93, v82, v83
	v_cvt_pk_bf16_f32 v94, v204, v205
	v_cvt_pk_bf16_f32 v95, v206, v207
	v_cvt_pk_bf16_f32 v80, v208, v209
	v_cvt_pk_bf16_f32 v81, v210, v211
	v_cvt_pk_bf16_f32 v82, v212, v213
	v_cvt_pk_bf16_f32 v83, v214, v215
	s_nop 0
	s_cmp_gt_i32 s18, 0
	s_cselect_b32 s20, -1, 2
	s_add_i32 s8, s8, s1
	s_add_i32 s20, s20, s18
	s_mov_b32 m0, s8
	s_add_u32 s98, s28, s74
	s_addc_u32 s99, s29, s75
	global_load_lds_dwordx4 v154, s[98:99]
	s_add_i32 m0, s8, 0x2000
	s_lshl_b32 s8, s20, 14
	s_add_i32 s8, s5, s8
	s_add_u32 s98, s28, s76
	s_addc_u32 s99, s29, s77
	global_load_lds_dwordx4 v154, s[98:99]
	s_mov_b32 m0, s8
	s_add_u32 s98, s28, s78
	s_addc_u32 s99, s29, s79
	global_load_lds_dwordx4 v152, s[98:99]
	s_add_i32 m0, s8, 0x2000
	s_nop 0
	s_add_u32 s98, s28, s80
	s_addc_u32 s99, s29, s81
	global_load_lds_dwordx4 v152, s[98:99]
	s_add_i32 m0, s19, s1
	s_nop 0
	s_add_u32 s98, s28, s82
	s_addc_u32 s99, s29, s83
	global_load_lds_dwordx4 v150, s[98:99]
	v_lshl_add_u32 v160, s18, 14, v166
	ds_read_b64_tr_b16 v[156:157], v160 offset:0
	ds_read_b64_tr_b16 v[158:159], v160 offset:0x800
	ds_read_b64_tr_b16 v[204:205], v160 offset:0x1000
	ds_read_b64_tr_b16 v[206:207], v160 offset:0x1800
	ds_read_b64_tr_b16 v[208:209], v160 offset:0x2000
	ds_read_b64_tr_b16 v[210:211], v160 offset:0x2800
	ds_read_b64_tr_b16 v[212:213], v160 offset:0x3000
	ds_read_b64_tr_b16 v[214:215], v160 offset:0x3800
	v_exp_f32_e32 v161, v104
	s_waitcnt lgkmcnt(0)
	s_add_i32 s8, s18, 1
	v_mfma_f32_32x32x16_bf16 v[48:63], v[84:87], v[156:159], v[48:63]
	ds_read_b64_tr_b16 v[156:157], v160 offset:0x200
	ds_read_b64_tr_b16 v[158:159], v160 offset:0xa00
	s_cmp_lg_u32 s18, 2
	s_cselect_b32 s18, s8, 0
	s_add_i32 s15, s15, 2
	v_lshl_add_u64 v[150:151], v[150:151], 0, s[84:85]
	v_lshl_add_u64 v[152:153], v[152:153], 0, s[86:87]
	v_mfma_f32_32x32x16_bf16 v[48:63], v[88:91], v[204:207], v[48:63]
	ds_read_b64_tr_b16 v[204:205], v160 offset:0x1200
	ds_read_b64_tr_b16 v[206:207], v160 offset:0x1a00
	v_lshl_add_u64 v[154:155], v[154:155], 0, s[86:87]
	s_cmpk_gt_u32 s15, 0x7c
	v_mfma_f32_32x32x16_bf16 v[48:63], v[92:95], v[208:211], v[48:63]
	ds_read_b64_tr_b16 v[208:209], v160 offset:0x2200
	ds_read_b64_tr_b16 v[210:211], v160 offset:0x2a00
	ds_read_b64_tr_b16 v[216:217], v160 offset:0x3200
	ds_read_b64_tr_b16 v[218:219], v160 offset:0x3a00
	s_nop 0
	s_waitcnt lgkmcnt(0)
	s_nop 0
	v_mfma_f32_32x32x16_bf16 v[32:47], v[84:87], v[156:159], v[32:47]
	ds_read_b64_tr_b16 v[156:157], v160 offset:0x400
	ds_read_b64_tr_b16 v[158:159], v160 offset:0xc00
	v_mfma_f32_32x32x16_bf16 v[32:47], v[88:91], v[204:207], v[32:47]
	ds_read_b64_tr_b16 v[204:205], v160 offset:0x1400
	ds_read_b64_tr_b16 v[206:207], v160 offset:0x1c00
	v_mfma_f32_32x32x16_bf16 v[32:47], v[92:95], v[208:211], v[32:47]
	ds_read_b64_tr_b16 v[208:209], v160 offset:0x2400
	ds_read_b64_tr_b16 v[210:211], v160 offset:0x2c00
	v_mfma_f32_32x32x16_bf16 v[48:63], v[80:83], v[212:215], v[48:63]
	ds_read_b64_tr_b16 v[212:213], v160 offset:0x3400
	ds_read_b64_tr_b16 v[214:215], v160 offset:0x3c00
	s_nop 0
	s_waitcnt lgkmcnt(0)
	v_mfma_f32_32x32x16_bf16 v[32:47], v[80:83], v[216:219], v[32:47]
	v_mfma_f32_32x32x16_bf16 v[16:31], v[84:87], v[156:159], v[16:31]
	ds_read_b64_tr_b16 v[156:157], v160 offset:0x600
	ds_read_b64_tr_b16 v[158:159], v160 offset:0xe00
	ds_read_b64_tr_b16 v[216:217], v160 offset:0x1600
	ds_read_b64_tr_b16 v[218:219], v160 offset:0x1e00
	ds_read_b64_tr_b16 v[220:221], v160 offset:0x2600
	ds_read_b64_tr_b16 v[222:223], v160 offset:0x2e00
	ds_read_b64_tr_b16 v[224:225], v160 offset:0x3600
	ds_read_b64_tr_b16 v[226:227], v160 offset:0x3e00
	v_mfma_f32_32x32x16_bf16 v[16:31], v[88:91], v[204:207], v[16:31]
	s_waitcnt lgkmcnt(0)
	v_exp_f32_e32 v206, v102
	v_exp_f32_e32 v207, v103
	v_exp_f32_e32 v205, v105
	v_exp_f32_e32 v160, v106
	v_exp_f32_e32 v204, v107
	v_mfma_f32_32x32x16_bf16 v[0:15], v[84:87], v[156:159], v[0:15]
	v_exp_f32_e32 v157, v108
	v_exp_f32_e32 v159, v109
	v_exp_f32_e32 v156, v110
	v_exp_f32_e32 v158, v111
	v_mfma_f32_32x32x16_bf16 v[0:15], v[88:91], v[216:219], v[0:15]
	v_mfma_f32_32x32x16_bf16 v[16:31], v[92:95], v[208:211], v[16:31]
	v_exp_f32_e32 v211, v96
	v_exp_f32_e32 v209, v98
	v_exp_f32_e32 v208, v100
	v_exp_f32_e32 v210, v101
	v_mfma_f32_32x32x16_bf16 v[0:15], v[92:95], v[220:223], v[0:15]
	v_mfma_f32_32x32x16_bf16 v[16:31], v[80:83], v[212:215], v[16:31]
	v_exp_f32_e32 v213, v97
	v_exp_f32_e32 v212, v99
	v_mfma_f32_32x32x16_bf16 v[0:15], v[80:83], v[224:227], v[0:15]
	s_cbranch_scc0 .LBB0_808
	s_and_b32 s0, s0, 0x3fffffc0
	s_waitcnt vmcnt(0)
	s_lshl_b32 s0, s0, 2
	s_waitcnt lgkmcnt(0)
	s_add_i32 s5, s0, 0
	s_add_i32 s5, s5, 0x18000
	s_barrier
	ds_read_b128 v[80:83], v192
	ds_read_b128 v[84:87], v192 offset:8192
	v_exp_f32_e32 v154, v64
	v_add_f32_e32 v64, 0, v211
	v_add_f32_e32 v64, v213, v64
	s_waitcnt lgkmcnt(0)
	v_mfma_f32_32x32x16_bf16 v[96:111], v[80:83], v[140:143], 0
	v_add_f32_e32 v64, v209, v64
	v_add_f32_e32 v64, v212, v64
	v_add_f32_e32 v64, v208, v64
	v_add_f32_e32 v64, v210, v64
	v_add_f32_e32 v64, v206, v64
	v_add_f32_e32 v64, v207, v64
	v_add_f32_e32 v64, v161, v64
	v_mfma_f32_32x32x16_bf16 v[80:95], v[84:87], v[140:143], 0
	ds_read_b128 v[140:143], v193
	ds_read_b128 v[150:153], v193 offset:8192
	v_add_f32_e32 v64, v205, v64
	v_add_f32_e32 v64, v160, v64
	v_add_f32_e32 v64, v204, v64
	v_add_f32_e32 v64, v157, v64
	v_exp_f32_e32 v155, v65
	v_add_f32_e32 v64, v159, v64
	s_waitcnt lgkmcnt(0)
	v_mfma_f32_32x32x16_bf16 v[96:111], v[140:143], v[136:139], v[96:111]
	v_add_f32_e32 v64, v156, v64
	v_add_f32_e32 v64, v158, v64
	v_add_f32_e32 v64, v154, v64
	v_add_f32_e32 v64, v155, v64
	v_exp_f32_e32 v218, v75
	v_exp_f32_e32 v79, v79
	v_cvt_pk_bf16_f32 v65, v209, v212
	v_mfma_f32_32x32x16_bf16 v[80:95], v[150:153], v[136:139], v[80:95]
	ds_read_b128 v[136:139], v194
	ds_read_b128 v[140:143], v194 offset:8192
	s_waitcnt lgkmcnt(0)
	v_mfma_f32_32x32x16_bf16 v[96:111], v[136:139], v[132:135], v[96:111]
	v_mfma_f32_32x32x16_bf16 v[80:95], v[140:143], v[132:135], v[80:95]
	ds_read_b128 v[132:135], v195
	ds_read_b128 v[136:139], v195 offset:8192
	s_waitcnt lgkmcnt(0)
	v_mfma_f32_32x32x16_bf16 v[96:111], v[132:135], v[128:131], v[96:111]
	v_mfma_f32_32x32x16_bf16 v[80:95], v[136:139], v[128:131], v[80:95]
	ds_read_b128 v[128:131], v196
	ds_read_b128 v[132:135], v196 offset:8192
	s_waitcnt lgkmcnt(0)
	v_mfma_f32_32x32x16_bf16 v[96:111], v[128:131], v[124:127], v[96:111]
	ds_read_b128 v[128:131], v197
	v_mfma_f32_32x32x16_bf16 v[80:95], v[132:135], v[124:127], v[80:95]
	ds_read_b128 v[124:127], v197 offset:8192
	ds_read_b128 v[132:135], v198
	ds_read_b128 v[136:139], v198 offset:8192
	ds_read_b128 v[140:143], v199
	ds_read_b128 v[150:153], v199 offset:8192
	ds_read_b128 v[168:171], v200
	ds_read_b128 v[172:175], v200 offset:4096
	v_exp_f32_e32 v200, v67
	v_cvt_pk_bf16_f32 v67, v206, v207
	s_nop 0
	s_waitcnt lgkmcnt(0)
	v_mfma_f32_32x32x16_bf16 v[96:111], v[128:131], v[120:123], v[96:111]
	ds_read_b128 v[128:131], v167
	ds_read_b128 v[176:179], v167 offset:8192
	ds_read_b128 v[180:183], v201
	ds_read_b128 v[184:187], v201 offset:4096
	ds_read_b128 v[188:191], v202
	ds_read_b128 v[192:195], v202 offset:4096
	ds_read_b128 v[196:199], v167 offset:16384
	ds_read_b128 v[214:217], v167 offset:24576
	v_exp_f32_e32 v167, v66
	v_exp_f32_e32 v201, v68
	v_exp_f32_e32 v202, v73
	v_cvt_pk_bf16_f32 v66, v208, v210
	v_add_f32_e32 v64, v167, v64
	v_add_f32_e32 v64, v200, v64
	v_mfma_f32_32x32x16_bf16 v[80:95], v[124:127], v[120:123], v[80:95]
	v_add_f32_e32 v64, v201, v64
	ds_read_b128 v[120:123], v203
	ds_read_b128 v[124:127], v203 offset:4096
	v_exp_f32_e32 v203, v74
	v_cvt_pk_bf16_f32 v68, v161, v205
	v_cvt_pk_bf16_f32 v73, v167, v200
	v_mfma_f32_32x32x16_bf16 v[96:111], v[132:135], v[116:119], v[96:111]
	v_exp_f32_e32 v132, v69
	v_exp_f32_e32 v133, v70
	v_exp_f32_e32 v134, v71
	v_exp_f32_e32 v135, v72
	v_add_f32_e32 v64, v132, v64
	v_add_f32_e32 v64, v133, v64
	v_add_f32_e32 v64, v134, v64
	v_mfma_f32_32x32x16_bf16 v[80:95], v[136:139], v[116:119], v[80:95]
	v_exp_f32_e32 v116, v76
	v_add_f32_e32 v64, v135, v64
	v_exp_f32_e32 v117, v77
	v_add_f32_e32 v64, v202, v64
	v_exp_f32_e32 v118, v78
	v_add_f32_e32 v64, v203, v64
	v_add_f32_e32 v64, v218, v64
	v_mfma_f32_32x32x16_bf16 v[96:111], v[140:143], v[112:115], v[96:111]
	v_add_f32_e32 v64, v116, v64
	v_add_f32_e32 v64, v117, v64
	v_add_f32_e32 v64, v118, v64
	v_cvt_pk_bf16_f32 v69, v160, v204
	v_cvt_pk_bf16_f32 v70, v157, v159
	v_cvt_pk_bf16_f32 v71, v156, v158
	v_cvt_pk_bf16_f32 v72, v154, v155
	v_mfma_f32_32x32x16_bf16 v[80:95], v[150:153], v[112:115], v[80:95]
	v_add_f32_e32 v112, v79, v64
	v_mov_b32_e32 v114, v112
	s_nop 1
	v_permlane32_swap_b32_e32 v112, v114
	v_cvt_pk_bf16_f32 v64, v211, v213
	v_cvt_pk_bf16_f32 v74, v201, v132
	v_cvt_pk_bf16_f32 v75, v133, v134
	s_waitcnt lgkmcnt(0)
	v_mfma_f32_32x32x16_bf16 v[96:111], v[168:171], v[128:131], v[96:111]
	v_cvt_pk_bf16_f32 v76, v135, v202
	v_cvt_pk_bf16_f32 v77, v203, v218
	v_cvt_pk_bf16_f32 v78, v116, v117
	v_cvt_pk_bf16_f32 v79, v118, v79
	v_mfma_f32_32x32x16_bf16 v[80:95], v[172:175], v[128:131], v[80:95]
	v_mfma_f32_32x32x16_bf16 v[96:111], v[180:183], v[176:179], v[96:111]
	v_mfma_f32_32x32x16_bf16 v[80:95], v[184:187], v[176:179], v[80:95]
	v_mfma_f32_32x32x16_bf16 v[96:111], v[188:191], v[196:199], v[96:111]
	v_mfma_f32_32x32x16_bf16 v[80:95], v[192:195], v[196:199], v[80:95]
	v_mfma_f32_32x32x16_bf16 v[96:111], v[120:123], v[214:217], v[96:111]
	v_mfma_f32_32x32x16_bf16 v[80:95], v[124:127], v[214:217], v[80:95]
	ds_read_b64_tr_b16 v[116:117], v166 offset:0
	ds_read_b64_tr_b16 v[118:119], v166 offset:0x800
	ds_read_b64_tr_b16 v[120:121], v166 offset:0x1000
	ds_read_b64_tr_b16 v[122:123], v166 offset:0x1800
	ds_read_b64_tr_b16 v[124:125], v166 offset:0x2000
	ds_read_b64_tr_b16 v[126:127], v166 offset:0x2800
	ds_read_b64_tr_b16 v[128:129], v166 offset:0x3000
	ds_read_b64_tr_b16 v[130:131], v166 offset:0x3800
	s_nop 10
	v_exp_f32_e32 v96, v96
	s_waitcnt lgkmcnt(0)
	v_exp_f32_e32 v97, v97
	v_mfma_f32_32x32x16_bf16 v[48:63], v[64:67], v[116:119], v[48:63]
	ds_read_b64_tr_b16 v[116:117], v166 offset:0x200
	ds_read_b64_tr_b16 v[118:119], v166 offset:0xa00
	ds_read_b64_tr_b16 v[132:133], v166 offset:0x1200
	ds_read_b64_tr_b16 v[134:135], v166 offset:0x1a00
	ds_read_b64_tr_b16 v[136:137], v166 offset:0x2200
	ds_read_b64_tr_b16 v[138:139], v166 offset:0x2a00
	v_exp_f32_e32 v98, v98
	v_mfma_f32_32x32x16_bf16 v[48:63], v[68:71], v[120:123], v[48:63]
	ds_read_b64_tr_b16 v[120:121], v166 offset:0x3200
	ds_read_b64_tr_b16 v[122:123], v166 offset:0x3a00
	v_exp_f32_e32 v99, v99
	s_waitcnt lgkmcnt(0)
	ds_read_b64_tr_b16 v[140:141], v166 offset:0x400
	ds_read_b64_tr_b16 v[142:143], v166 offset:0xc00
	ds_read_b64_tr_b16 v[150:151], v166 offset:0x1400
	v_mfma_f32_32x32x16_bf16 v[48:63], v[72:75], v[124:127], v[48:63]
	ds_read_b64_tr_b16 v[152:153], v166 offset:0x1c00
	ds_read_b64_tr_b16 v[124:125], v166 offset:0x2400
	ds_read_b64_tr_b16 v[126:127], v166 offset:0x2c00
	ds_read_b64_tr_b16 v[154:155], v166 offset:0x3400
	ds_read_b64_tr_b16 v[156:157], v166 offset:0x3c00
	v_exp_f32_e32 v100, v100
	s_waitcnt lgkmcnt(0)
	v_add_f32_e32 v113, 0, v96
	v_mfma_f32_32x32x16_bf16 v[48:63], v[76:79], v[128:131], v[48:63]
	ds_read_b64_tr_b16 v[128:129], v166 offset:0x600
	ds_read_b64_tr_b16 v[130:131], v166 offset:0xe00
	ds_read_b64_tr_b16 v[158:159], v166 offset:0x1600
	ds_read_b64_tr_b16 v[160:161], v166 offset:0x1e00
	ds_read_b64_tr_b16 v[168:169], v166 offset:0x2600
	ds_read_b64_tr_b16 v[170:171], v166 offset:0x2e00
	ds_read_b64_tr_b16 v[172:173], v166 offset:0x3600
	ds_read_b64_tr_b16 v[174:175], v166 offset:0x3e00
	v_exp_f32_e32 v101, v101
	v_add_f32_e32 v113, v97, v113
	v_mfma_f32_32x32x16_bf16 v[32:47], v[64:67], v[116:119], v[32:47]
	s_waitcnt lgkmcnt(0)
	v_exp_f32_e32 v102, v102
	v_add_f32_e32 v113, v98, v113
	v_exp_f32_e32 v103, v103
	v_add_f32_e32 v113, v99, v113
	v_exp_f32_e32 v104, v104
	v_add_f32_e32 v113, v100, v113
	v_mfma_f32_32x32x16_bf16 v[16:31], v[64:67], v[140:143], v[16:31]
	v_exp_f32_e32 v105, v105
	v_add_f32_e32 v113, v101, v113
	v_exp_f32_e32 v106, v106
	v_add_f32_e32 v113, v102, v113
	v_exp_f32_e32 v107, v107
	v_add_f32_e32 v113, v103, v113
	v_exp_f32_e32 v108, v108
	v_mfma_f32_32x32x16_bf16 v[0:15], v[64:67], v[128:131], v[0:15]
	v_add_f32_e32 v113, v104, v113
	v_exp_f32_e32 v109, v109
	v_add_f32_e32 v113, v105, v113
	v_exp_f32_e32 v110, v110
	v_add_f32_e32 v113, v106, v113
	v_exp_f32_e32 v111, v111
	v_add_f32_e32 v113, v107, v113
	v_mfma_f32_32x32x16_bf16 v[32:47], v[68:71], v[132:135], v[32:47]
	v_exp_f32_e32 v80, v80
	v_add_f32_e32 v113, v108, v113
	v_exp_f32_e32 v81, v81
	v_add_f32_e32 v113, v109, v113
	v_exp_f32_e32 v82, v82
	v_add_f32_e32 v113, v110, v113
	v_exp_f32_e32 v83, v83
	v_mfma_f32_32x32x16_bf16 v[16:31], v[68:71], v[150:153], v[16:31]
	v_add_f32_e32 v113, v111, v113
	v_exp_f32_e32 v84, v84
	v_add_f32_e32 v113, v80, v113
	v_exp_f32_e32 v85, v85
	v_add_f32_e32 v113, v81, v113
	v_exp_f32_e32 v86, v86
	v_add_f32_e32 v113, v82, v113
	v_mfma_f32_32x32x16_bf16 v[0:15], v[68:71], v[158:161], v[0:15]
	v_exp_f32_e32 v87, v87
	v_add_f32_e32 v113, v83, v113
	v_exp_f32_e32 v88, v88
	v_add_f32_e32 v113, v84, v113
	v_exp_f32_e32 v89, v89
	v_add_f32_e32 v113, v85, v113
	v_exp_f32_e32 v90, v90
	v_mfma_f32_32x32x16_bf16 v[32:47], v[72:75], v[136:139], v[32:47]
	v_add_f32_e32 v64, v86, v113
	v_exp_f32_e32 v91, v91
	v_add_f32_e32 v64, v87, v64
	v_exp_f32_e32 v92, v92
	v_add_f32_e32 v64, v88, v64
	v_exp_f32_e32 v93, v93
	v_add_f32_e32 v64, v89, v64
	v_mfma_f32_32x32x16_bf16 v[16:31], v[72:75], v[124:127], v[16:31]
	v_exp_f32_e32 v94, v94
	v_add_f32_e32 v64, v90, v64
	v_exp_f32_e32 v95, v95
	v_add_f32_e32 v64, v91, v64
	v_add_f32_e32 v64, v92, v64
	v_add_f32_e32 v64, v93, v64
	v_add_f32_e32 v64, v94, v64
	v_mfma_f32_32x32x16_bf16 v[0:15], v[72:75], v[168:171], v[0:15]
	v_add_f32_e32 v113, v95, v64
	v_mov_b32_e32 v115, v113
	s_nop 1
	v_permlane32_swap_b32_e32 v113, v115
	v_cvt_pk_bf16_f32 v64, v96, v97
	v_cvt_pk_bf16_f32 v65, v98, v99
	v_cvt_pk_bf16_f32 v66, v100, v101
	v_mfma_f32_32x32x16_bf16 v[32:47], v[76:79], v[120:123], v[32:47]
	v_cvt_pk_bf16_f32 v67, v102, v103
	v_cvt_pk_bf16_f32 v68, v104, v105
	v_cvt_pk_bf16_f32 v69, v106, v107
	v_cvt_pk_bf16_f32 v70, v108, v109
	v_cvt_pk_bf16_f32 v71, v110, v111
	v_cvt_pk_bf16_f32 v72, v80, v81
	v_cvt_pk_bf16_f32 v73, v82, v83
	v_mfma_f32_32x32x16_bf16 v[16:31], v[76:79], v[154:157], v[16:31]
	v_cvt_pk_bf16_f32 v74, v84, v85
	v_cvt_pk_bf16_f32 v75, v86, v87
	v_mfma_f32_32x32x16_bf16 v[0:15], v[76:79], v[172:175], v[0:15]
	v_cvt_pk_bf16_f32 v76, v88, v89
	v_cvt_pk_bf16_f32 v77, v90, v91
	v_cvt_pk_bf16_f32 v78, v92, v93
	v_cvt_pk_bf16_f32 v79, v94, v95
	s_cmp_lg_u32 0, -1
	s_cselect_b32 s0, 0, 0
	s_addk_i32 s0, 0x4000
	v_add_u32_e32 v100, s0, v165
	ds_read_b64_tr_b16 v[80:81], v100 offset:0
	ds_read_b64_tr_b16 v[82:83], v100 offset:0x800
	ds_read_b64_tr_b16 v[84:85], v100 offset:0x1000
	ds_read_b64_tr_b16 v[86:87], v100 offset:0x1800
	ds_read_b64_tr_b16 v[88:89], v100 offset:0x2000
	ds_read_b64_tr_b16 v[90:91], v100 offset:0x2800
	ds_read_b64_tr_b16 v[92:93], v100 offset:0x3000
	ds_read_b64_tr_b16 v[94:95], v100 offset:0x3800
	s_nop 0
	s_waitcnt lgkmcnt(0)
	s_nop 0
	v_mfma_f32_32x32x16_bf16 v[48:63], v[64:67], v[80:83], v[48:63]
	ds_read_b64_tr_b16 v[80:81], v100 offset:0x200
	ds_read_b64_tr_b16 v[82:83], v100 offset:0xa00
	v_mfma_f32_32x32x16_bf16 v[48:63], v[68:71], v[84:87], v[48:63]
	ds_read_b64_tr_b16 v[84:85], v100 offset:0x1200
	ds_read_b64_tr_b16 v[86:87], v100 offset:0x1a00
	v_mfma_f32_32x32x16_bf16 v[48:63], v[72:75], v[88:91], v[48:63]
	ds_read_b64_tr_b16 v[88:89], v100 offset:0x2200
	ds_read_b64_tr_b16 v[90:91], v100 offset:0x2a00
	ds_read_b64_tr_b16 v[96:97], v100 offset:0x3200
	ds_read_b64_tr_b16 v[98:99], v100 offset:0x3a00
	s_nop 0
	s_waitcnt lgkmcnt(0)
	s_nop 0
	v_mfma_f32_32x32x16_bf16 v[32:47], v[64:67], v[80:83], v[32:47]
	ds_read_b64_tr_b16 v[80:81], v100 offset:0x400
	ds_read_b64_tr_b16 v[82:83], v100 offset:0xc00
	v_mfma_f32_32x32x16_bf16 v[32:47], v[68:71], v[84:87], v[32:47]
	ds_read_b64_tr_b16 v[84:85], v100 offset:0x1400
	ds_read_b64_tr_b16 v[86:87], v100 offset:0x1c00
	v_mfma_f32_32x32x16_bf16 v[48:63], v[76:79], v[92:95], v[48:63]
	v_mfma_f32_32x32x16_bf16 v[32:47], v[72:75], v[88:91], v[32:47]
	ds_read_b64_tr_b16 v[88:89], v100 offset:0x2400
	ds_read_b64_tr_b16 v[90:91], v100 offset:0x2c00
	ds_read_b64_tr_b16 v[92:93], v100 offset:0x3400
	ds_read_b64_tr_b16 v[94:95], v100 offset:0x3c00
	s_nop 0
	s_waitcnt lgkmcnt(0)
	s_nop 0
	v_mfma_f32_32x32x16_bf16 v[16:31], v[64:67], v[80:83], v[16:31]
	ds_read_b64_tr_b16 v[80:81], v100 offset:0x600
	ds_read_b64_tr_b16 v[82:83], v100 offset:0xe00
	v_mfma_f32_32x32x16_bf16 v[16:31], v[68:71], v[84:87], v[16:31]
	ds_read_b64_tr_b16 v[84:85], v100 offset:0x1600
	ds_read_b64_tr_b16 v[86:87], v100 offset:0x1e00
	v_mfma_f32_32x32x16_bf16 v[16:31], v[72:75], v[88:91], v[16:31]
	ds_read_b64_tr_b16 v[88:89], v100 offset:0x2600
	ds_read_b64_tr_b16 v[90:91], v100 offset:0x2e00
	v_mfma_f32_32x32x16_bf16 v[16:31], v[76:79], v[92:95], v[16:31]
	ds_read_b64_tr_b16 v[92:93], v100 offset:0x3600
	ds_read_b64_tr_b16 v[94:95], v100 offset:0x3e00
	s_nop 0
	s_waitcnt lgkmcnt(0)
	s_nop 0
	v_mfma_f32_32x32x16_bf16 v[0:15], v[64:67], v[80:83], v[0:15]
	v_mfma_f32_32x32x16_bf16 v[0:15], v[68:71], v[84:87], v[0:15]
	v_mfma_f32_32x32x16_bf16 v[0:15], v[72:75], v[88:91], v[0:15]
	v_mfma_f32_32x32x16_bf16 v[32:47], v[76:79], v[96:99], v[32:47]
	v_mfma_f32_32x32x16_bf16 v[0:15], v[76:79], v[92:95], v[0:15]
	s_setprio 0
	v_cmp_gt_u32_e32 vcc, 32, v149
	s_and_saveexec_b64 s[0:1], vcc
	s_cbranch_execz .LBB0_781
	v_pk_add_f32 v[64:65], v[112:113], v[114:115]
	v_lshl_add_u32 v66, v162, 2, s5
	v_add_f32_e32 v64, v146, v64
	v_add_f32_e32 v64, v64, v65
	ds_write_b32 v66, v64
	s_branch .LBB0_781

.LBB0_873:
	s_lshl_b32 s44, s50, 8
	s_add_i32 s44, s45, s44
	v_lshl_or_b32 v128, v134, 3, s2
	s_ashr_i32 s2, s44, 13
	v_or_b32_e32 v132, s46, v128
	s_mul_i32 s46, s2, 0xc00
	s_ashr_i32 s47, s46, 31
	s_lshl_b64 s[46:47], s[46:47], 2
	v_or_b32_e32 v138, s44, v148
	s_add_u32 s46, s28, s46
	v_ashrrev_i32_e32 v139, 31, v138
	v_readlane_b32 s64, v237, 1
	s_addc_u32 s47, s29, s47
	v_lshlrev_b64 v[128:129], 2, v[132:133]
	v_lshlrev_b64 v[134:135], 12, v[138:139]
	v_readlane_b32 s78, v237, 15
	v_readlane_b32 s79, v237, 16
	v_lshl_add_u64 v[130:131], s[46:47], 0, v[128:129]
	v_mov_b32 v136, 0
	v_lshl_add_u64 v[142:143], v[130:131], 0, s[42:43]
	v_lshl_add_u64 v[134:135], s[78:79], 0, v[134:135]
	v_lshl_add_u64 v[134:135], v[134:135], 0, v[128:129]
	v_add_co_u32_e32 v128, vcc, s59, v130
	v_readlane_b32 s65, v237, 2
	s_nop 0
	v_addc_co_u32_e32 v129, vcc, 0, v131, vcc
	global_load_dwordx4 v[208:211], v[128:129], off
	global_load_dwordx4 v[212:215], v[134:135], off offset:16
	global_load_dwordx4 v[216:219], v[134:135], off
	global_load_dwordx4 v[220:223], v[142:143], off offset:16
	global_load_dwordx4 v[224:227], v[142:143], off offset:80
	global_load_dwordx4 v[228:231], v[142:143], off offset:64
	global_load_dwordx4 v[232:235], v[134:135], off offset:64
	global_load_dwordx4 v[238:241], v[134:135], off offset:80
	global_load_dwordx4 v[242:245], v[142:143], off offset:144
	global_load_dwordx4 v[246:249], v[142:143], off offset:128
	global_load_dwordx4 v[250:253], v[134:135], off offset:128
	global_load_dwordx4 v[150:153], v[134:135], off offset:144
	v_cmp_ne_u32_e32 vcc, 0, v136
	v_readlane_b32 s66, v237, 3
	v_readlane_b32 s67, v237, 4
	v_readlane_b32 s68, v237, 5
	v_readlane_b32 s69, v237, 6
	v_readlane_b32 s70, v237, 7
	v_readlane_b32 s71, v237, 8
	v_readlane_b32 s72, v237, 9
	v_readlane_b32 s73, v237, 10
	v_readlane_b32 s74, v237, 11
	v_readlane_b32 s75, v237, 12
	v_readlane_b32 s76, v237, 13
	v_readlane_b32 s77, v237, 14
	s_waitcnt vmcnt(8)
	v_pk_fma_f32 v[128:129], v[112:113], v[208:209], v[216:217]
	v_pk_fma_f32 v[112:113], v[120:121], v[220:221], v[212:213]
	v_pk_fma_f32 v[130:131], v[114:115], v[210:211], v[218:219]
	v_pk_fma_f32 v[114:115], v[122:123], v[222:223], v[214:215]
	global_load_dwordx4 v[208:211], v[142:143], off offset:208
	global_load_dwordx4 v[212:215], v[142:143], off offset:192
	global_load_dwordx4 v[216:219], v[134:135], off offset:192
	global_load_dwordx4 v[220:223], v[134:135], off offset:208
	s_waitcnt vmcnt(8)
	v_pk_fma_f32 v[120:121], v[116:117], v[228:229], v[232:233]
	v_pk_fma_f32 v[116:117], v[124:125], v[224:225], v[238:239]
	v_pk_fma_f32 v[122:123], v[118:119], v[230:231], v[234:235]
	v_pk_fma_f32 v[118:119], v[126:127], v[226:227], v[240:241]
	global_load_dwordx4 v[224:227], v[142:143], off offset:272
	global_load_dwordx4 v[228:231], v[142:143], off offset:256
	global_load_dwordx4 v[232:235], v[134:135], off offset:256
	global_load_dwordx4 v[238:241], v[134:135], off offset:272
	s_waitcnt vmcnt(8)
	v_pk_fma_f32 v[124:125], v[96:97], v[246:247], v[250:251]
	v_pk_fma_f32 v[96:97], v[104:105], v[242:243], v[150:151]
	v_pk_fma_f32 v[126:127], v[98:99], v[248:249], v[252:253]
	v_pk_fma_f32 v[98:99], v[106:107], v[244:245], v[152:153]
	global_load_dwordx4 v[242:245], v[142:143], off offset:336
	global_load_dwordx4 v[246:249], v[142:143], off offset:320
	global_load_dwordx4 v[250:253], v[134:135], off offset:320
	global_load_dwordx4 v[150:153], v[134:135], off offset:336
	s_waitcnt vmcnt(8)
	v_pk_fma_f32 v[104:105], v[100:101], v[212:213], v[216:217]
	v_pk_fma_f32 v[100:101], v[108:109], v[208:209], v[220:221]
	v_pk_fma_f32 v[106:107], v[102:103], v[214:215], v[218:219]
	v_pk_fma_f32 v[102:103], v[110:111], v[210:211], v[222:223]
	global_load_dwordx4 v[208:211], v[142:143], off offset:400
	global_load_dwordx4 v[212:215], v[142:143], off offset:384
	global_load_dwordx4 v[216:219], v[134:135], off offset:384
	global_load_dwordx4 v[220:223], v[134:135], off offset:400
	s_waitcnt vmcnt(8)
	v_pk_fma_f32 v[108:109], v[80:81], v[228:229], v[232:233]
	v_pk_fma_f32 v[80:81], v[88:89], v[224:225], v[238:239]
	v_pk_fma_f32 v[110:111], v[82:83], v[230:231], v[234:235]
	v_pk_fma_f32 v[82:83], v[90:91], v[226:227], v[240:241]
	global_load_dwordx4 v[224:227], v[142:143], off offset:464
	global_load_dwordx4 v[228:231], v[142:143], off offset:448
	global_load_dwordx4 v[232:235], v[134:135], off offset:448
	global_load_dwordx4 v[238:241], v[134:135], off offset:464
	s_waitcnt vmcnt(8)
	v_pk_fma_f32 v[88:89], v[84:85], v[246:247], v[250:251]
	v_pk_fma_f32 v[84:85], v[92:93], v[242:243], v[150:151]
	v_pk_fma_f32 v[90:91], v[86:87], v[248:249], v[252:253]
	v_pk_fma_f32 v[86:87], v[94:95], v[244:245], v[152:153]
	s_waitcnt vmcnt(4)
	v_pk_fma_f32 v[92:93], v[64:65], v[212:213], v[216:217]
	v_pk_fma_f32 v[64:65], v[72:73], v[208:209], v[220:221]
	v_pk_fma_f32 v[94:95], v[66:67], v[214:215], v[218:219]
	v_pk_fma_f32 v[66:67], v[74:75], v[210:211], v[222:223]
	s_waitcnt vmcnt(0)
	v_pk_fma_f32 v[72:73], v[68:69], v[228:229], v[232:233]
	v_pk_fma_f32 v[68:69], v[76:77], v[224:225], v[238:239]
	v_pk_fma_f32 v[74:75], v[70:71], v[230:231], v[234:235]
	v_pk_fma_f32 v[70:71], v[78:79], v[226:227], v[240:241]
	v_or_b32_e32 v140, 32, v138
	v_ashrrev_i32_e32 v141, 31, v140
	v_readlane_b32 s64, v237, 1
	v_lshlrev_b64 v[76:77], 12, v[140:141]
	v_readlane_b32 s78, v237, 15
	v_readlane_b32 s79, v237, 16
	v_readlane_b32 s65, v237, 2
	v_readlane_b32 s66, v237, 3
	v_lshl_add_u64 v[76:77], s[78:79], 0, v[76:77]
	v_lshl_add_u64 v[136:137], v[132:133], 2, v[76:77]
	global_load_dwordx4 v[242:245], v[142:143], off offset:16
	global_load_dwordx4 v[246:249], v[142:143], off
	global_load_dwordx4 v[250:253], v[136:137], off
	global_load_dwordx4 v[150:153], v[136:137], off offset:16
	global_load_dwordx4 v[208:211], v[142:143], off offset:80
	global_load_dwordx4 v[212:215], v[142:143], off offset:64
	global_load_dwordx4 v[216:219], v[136:137], off offset:64
	global_load_dwordx4 v[220:223], v[136:137], off offset:80
	global_load_dwordx4 v[224:227], v[142:143], off offset:144
	global_load_dwordx4 v[228:231], v[142:143], off offset:128
	global_load_dwordx4 v[232:235], v[136:137], off offset:128
	global_load_dwordx4 v[238:241], v[136:137], off offset:144
	v_readlane_b32 s67, v237, 4
	v_readlane_b32 s68, v237, 5
	v_readlane_b32 s69, v237, 6
	v_readlane_b32 s70, v237, 7
	v_readlane_b32 s71, v237, 8
	v_readlane_b32 s72, v237, 9
	v_readlane_b32 s73, v237, 10
	v_readlane_b32 s74, v237, 11
	v_readlane_b32 s75, v237, 12
	v_readlane_b32 s76, v237, 13
	v_readlane_b32 s77, v237, 14
	s_waitcnt vmcnt(8)
	v_pk_fma_f32 v[76:77], v[48:49], v[246:247], v[250:251]
	v_pk_fma_f32 v[48:49], v[56:57], v[242:243], v[150:151]
	v_pk_fma_f32 v[78:79], v[50:51], v[248:249], v[252:253]
	v_pk_fma_f32 v[50:51], v[58:59], v[244:245], v[152:153]
	global_load_dwordx4 v[242:245], v[142:143], off offset:208
	global_load_dwordx4 v[246:249], v[142:143], off offset:192
	global_load_dwordx4 v[250:253], v[136:137], off offset:192
	global_load_dwordx4 v[150:153], v[136:137], off offset:208
	s_waitcnt vmcnt(8)
	v_pk_fma_f32 v[56:57], v[52:53], v[212:213], v[216:217]
	v_pk_fma_f32 v[52:53], v[60:61], v[208:209], v[220:221]
	v_pk_fma_f32 v[58:59], v[54:55], v[214:215], v[218:219]
	v_pk_fma_f32 v[54:55], v[62:63], v[210:211], v[222:223]
	global_load_dwordx4 v[208:211], v[142:143], off offset:272
	global_load_dwordx4 v[212:215], v[142:143], off offset:256
	global_load_dwordx4 v[216:219], v[136:137], off offset:256
	global_load_dwordx4 v[220:223], v[136:137], off offset:272
	s_waitcnt vmcnt(8)
	v_pk_fma_f32 v[60:61], v[32:33], v[228:229], v[232:233]
	v_pk_fma_f32 v[32:33], v[40:41], v[224:225], v[238:239]
	v_pk_fma_f32 v[62:63], v[34:35], v[230:231], v[234:235]
	v_pk_fma_f32 v[34:35], v[42:43], v[226:227], v[240:241]
	global_load_dwordx4 v[224:227], v[142:143], off offset:336
	global_load_dwordx4 v[228:231], v[142:143], off offset:320
	global_load_dwordx4 v[232:235], v[136:137], off offset:320
	global_load_dwordx4 v[238:241], v[136:137], off offset:336
	s_waitcnt vmcnt(8)
	v_pk_fma_f32 v[40:41], v[36:37], v[246:247], v[250:251]
	v_pk_fma_f32 v[36:37], v[44:45], v[242:243], v[150:151]
	v_pk_fma_f32 v[42:43], v[38:39], v[248:249], v[252:253]
	v_pk_fma_f32 v[38:39], v[46:47], v[244:245], v[152:153]
	global_load_dwordx4 v[242:245], v[142:143], off offset:400
	global_load_dwordx4 v[246:249], v[142:143], off offset:384
	global_load_dwordx4 v[250:253], v[136:137], off offset:384
	global_load_dwordx4 v[150:153], v[136:137], off offset:400
	s_waitcnt vmcnt(8)
	v_pk_fma_f32 v[44:45], v[16:17], v[212:213], v[216:217]
	v_pk_fma_f32 v[16:17], v[24:25], v[208:209], v[220:221]
	v_pk_fma_f32 v[46:47], v[18:19], v[214:215], v[218:219]
	v_pk_fma_f32 v[18:19], v[26:27], v[210:211], v[222:223]
	global_load_dwordx4 v[208:211], v[142:143], off offset:464
	global_load_dwordx4 v[212:215], v[142:143], off offset:448
	global_load_dwordx4 v[216:219], v[136:137], off offset:448
	global_load_dwordx4 v[220:223], v[136:137], off offset:464
	s_waitcnt vmcnt(8)
	v_pk_fma_f32 v[24:25], v[20:21], v[228:229], v[232:233]
	v_pk_fma_f32 v[20:21], v[28:29], v[224:225], v[238:239]
	v_pk_fma_f32 v[26:27], v[22:23], v[230:231], v[234:235]
	v_pk_fma_f32 v[22:23], v[30:31], v[226:227], v[240:241]
	s_waitcnt vmcnt(4)
	v_pk_fma_f32 v[28:29], v[0:1], v[246:247], v[250:251]
	v_pk_fma_f32 v[0:1], v[8:9], v[242:243], v[150:151]
	v_pk_fma_f32 v[30:31], v[2:3], v[248:249], v[252:253]
	v_pk_fma_f32 v[2:3], v[10:11], v[244:245], v[152:153]
	s_waitcnt vmcnt(0)
	v_pk_fma_f32 v[8:9], v[4:5], v[212:213], v[216:217]
	v_pk_fma_f32 v[4:5], v[12:13], v[208:209], v[220:221]
	v_pk_fma_f32 v[10:11], v[6:7], v[214:215], v[218:219]
	v_pk_fma_f32 v[6:7], v[14:15], v[210:211], v[222:223]
	s_ashr_i32 s45, s44, 31
	v_cmp_gt_u32_e32 vcc, 32, v149
	v_pk_mul_f32 v[12:13], v[128:129], v[128:129]
	v_pk_mul_f32 v[14:15], v[130:131], v[130:131]
	v_add_f32_e32 v12, v12, v13
	v_add_f32_e32 v12, v14, v12
	v_pk_mul_f32 v[142:143], v[120:121], v[120:121]
	v_add_f32_e32 v12, v15, v12
	v_add_f32_e32 v12, v12, v142
	v_pk_mul_f32 v[150:151], v[122:123], v[122:123]
	v_add_f32_e32 v12, v143, v12
	v_add_f32_e32 v12, v150, v12
	v_pk_mul_f32 v[152:153], v[112:113], v[112:113]
	v_add_f32_e32 v12, v151, v12
	v_add_f32_e32 v12, v152, v12
	v_pk_mul_f32 v[154:155], v[114:115], v[114:115]
	v_add_f32_e32 v12, v153, v12
	v_add_f32_e32 v12, v154, v12
	v_pk_mul_f32 v[156:157], v[116:117], v[116:117]
	v_add_f32_e32 v12, v155, v12
	v_add_f32_e32 v12, v156, v12
	v_pk_mul_f32 v[158:159], v[118:119], v[118:119]
	v_add_f32_e32 v12, v157, v12
	v_add_f32_e32 v12, v158, v12
	v_pk_mul_f32 v[160:161], v[124:125], v[124:125]
	v_add_f32_e32 v12, v159, v12
	v_add_f32_e32 v12, v12, v160
	v_pk_mul_f32 v[162:163], v[126:127], v[126:127]
	v_add_f32_e32 v12, v161, v12
	v_add_f32_e32 v12, v162, v12
	v_pk_mul_f32 v[164:165], v[104:105], v[104:105]
	v_add_f32_e32 v12, v163, v12
	v_add_f32_e32 v12, v12, v164
	v_pk_mul_f32 v[166:167], v[106:107], v[106:107]
	v_add_f32_e32 v12, v165, v12
	v_add_f32_e32 v12, v166, v12
	v_pk_mul_f32 v[168:169], v[96:97], v[96:97]
	v_add_f32_e32 v12, v167, v12
	v_add_f32_e32 v12, v168, v12
	v_pk_mul_f32 v[170:171], v[98:99], v[98:99]
	v_add_f32_e32 v12, v169, v12
	v_add_f32_e32 v12, v170, v12
	v_pk_mul_f32 v[172:173], v[100:101], v[100:101]
	v_add_f32_e32 v12, v171, v12
	v_add_f32_e32 v12, v172, v12
	v_pk_mul_f32 v[174:175], v[102:103], v[102:103]
	v_add_f32_e32 v12, v173, v12
	v_add_f32_e32 v12, v174, v12
	v_pk_mul_f32 v[176:177], v[108:109], v[108:109]
	v_add_f32_e32 v12, v175, v12
	v_add_f32_e32 v12, v12, v176
	v_pk_mul_f32 v[178:179], v[110:111], v[110:111]
	v_add_f32_e32 v12, v177, v12
	v_add_f32_e32 v12, v178, v12
	v_pk_mul_f32 v[180:181], v[88:89], v[88:89]
	v_add_f32_e32 v12, v179, v12
	v_add_f32_e32 v12, v12, v180
	v_pk_mul_f32 v[182:183], v[90:91], v[90:91]
	v_add_f32_e32 v12, v181, v12
	v_add_f32_e32 v12, v182, v12
	v_pk_mul_f32 v[184:185], v[80:81], v[80:81]
	v_add_f32_e32 v12, v183, v12
	v_add_f32_e32 v12, v184, v12
	v_pk_mul_f32 v[186:187], v[82:83], v[82:83]
	v_add_f32_e32 v12, v185, v12
	v_add_f32_e32 v12, v186, v12
	v_pk_mul_f32 v[188:189], v[84:85], v[84:85]
	v_add_f32_e32 v12, v187, v12
	v_add_f32_e32 v12, v188, v12
	v_pk_mul_f32 v[190:191], v[86:87], v[86:87]
	v_add_f32_e32 v12, v189, v12
	v_add_f32_e32 v12, v190, v12
	v_pk_mul_f32 v[192:193], v[92:93], v[92:93]
	v_add_f32_e32 v12, v191, v12
	v_add_f32_e32 v12, v12, v192
	v_pk_mul_f32 v[194:195], v[94:95], v[94:95]
	v_add_f32_e32 v12, v193, v12
	v_add_f32_e32 v12, v194, v12
	v_pk_mul_f32 v[196:197], v[72:73], v[72:73]
	v_add_f32_e32 v12, v195, v12
	v_add_f32_e32 v12, v12, v196
	v_pk_mul_f32 v[198:199], v[74:75], v[74:75]
	v_add_f32_e32 v12, v197, v12
	v_add_f32_e32 v12, v198, v12
	v_pk_mul_f32 v[200:201], v[64:65], v[64:65]
	v_add_f32_e32 v12, v199, v12
	v_add_f32_e32 v12, v200, v12
	v_pk_mul_f32 v[202:203], v[66:67], v[66:67]
	v_add_f32_e32 v12, v201, v12
	v_add_f32_e32 v12, v202, v12
	v_pk_mul_f32 v[204:205], v[68:69], v[68:69]
	v_add_f32_e32 v12, v203, v12
	v_add_f32_e32 v12, v204, v12
	v_pk_mul_f32 v[206:207], v[70:71], v[70:71]
	v_add_f32_e32 v12, v205, v12
	v_add_f32_e32 v12, v206, v12
	v_add_f32_e32 v14, v207, v12
	ds_bpermute_b32 v15, v145, v14
	s_lshl_b64 s[44:45], s[44:45], 2
	s_add_u32 s44, s0, s44
	s_addc_u32 s45, s1, s45
	v_lshlrev_b32_e32 v12, 2, v148
	v_mov_b32_e32 v13, v133
	v_lshl_add_u64 v[12:13], s[44:45], 0, v[12:13]
	s_and_saveexec_b64 s[44:45], vcc
	s_cbranch_execz .LBB0_907
	s_waitcnt lgkmcnt(0)
	v_add_f32_e32 v14, v14, v15
	global_atomic_add_f32 v[12:13], v14, off

	.amdhsa_kernel _Z4mega6Params
		.amdhsa_group_segment_fixed_size 0
		.amdhsa_private_segment_fixed_size 0
		.amdhsa_kernarg_size 456
		.amdhsa_user_sgpr_count 2
		.amdhsa_user_sgpr_dispatch_ptr 0
		.amdhsa_user_sgpr_queue_ptr 0
		.amdhsa_user_sgpr_kernarg_segment_ptr 1
		.amdhsa_user_sgpr_dispatch_id 0
		.amdhsa_user_sgpr_kernarg_preload_length 0
		.amdhsa_user_sgpr_kernarg_preload_offset 0
		.amdhsa_user_sgpr_private_segment_size 0
		.amdhsa_uses_dynamic_stack 0
		.amdhsa_enable_private_segment 0
		.amdhsa_system_sgpr_workgroup_id_x 1
		.amdhsa_system_sgpr_workgroup_id_y 0
		.amdhsa_system_sgpr_workgroup_id_z 0
		.amdhsa_system_sgpr_workgroup_info 0
		.amdhsa_system_vgpr_workitem_id 2
		.amdhsa_next_free_vgpr 256
		.amdhsa_next_free_sgpr 100
		.amdhsa_accum_offset 256
		.amdhsa_reserve_vcc 1
		.amdhsa_float_round_mode_32 0
		.amdhsa_float_round_mode_16_64 0
		.amdhsa_float_denorm_mode_32 3
		.amdhsa_float_denorm_mode_16_64 3
		.amdhsa_dx10_clamp 1
		.amdhsa_ieee_mode 1
		.amdhsa_fp16_overflow 0
		.amdhsa_tg_split 0
		.amdhsa_exception_fp_ieee_invalid_op 0
		.amdhsa_exception_fp_denorm_src 0
		.amdhsa_exception_fp_ieee_div_zero 0
		.amdhsa_exception_fp_ieee_overflow 0
		.amdhsa_exception_fp_ieee_underflow 0
		.amdhsa_exception_fp_ieee_inexact 0
		.amdhsa_exception_int_div_zero 0
	.end_amdhsa_kernel

amdhsa.kernels:
  - .agpr_count:     0
    .args:
      - .offset:         0
        .size:           200
        .value_kind:     by_value
      - .offset:         200
        .size:           4
        .value_kind:     hidden_block_count_x
      - .offset:         204
        .size:           4
        .value_kind:     hidden_block_count_y
      - .offset:         208
        .size:           4
        .value_kind:     hidden_block_count_z
      - .offset:         212
        .size:           2
        .value_kind:     hidden_group_size_x
      - .offset:         214
        .size:           2
        .value_kind:     hidden_group_size_y
      - .offset:         216
        .size:           2
        .value_kind:     hidden_group_size_z
      - .offset:         218
        .size:           2
        .value_kind:     hidden_remainder_x
      - .offset:         220
        .size:           2
        .value_kind:     hidden_remainder_y
      - .offset:         222
        .size:           2
        .value_kind:     hidden_remainder_z
      - .offset:         240
        .size:           8
        .value_kind:     hidden_global_offset_x
      - .offset:         248
        .size:           8
        .value_kind:     hidden_global_offset_y
      - .offset:         256
        .size:           8
        .value_kind:     hidden_global_offset_z
      - .offset:         264
        .size:           2
        .value_kind:     hidden_grid_dims
      - .offset:         288
        .size:           8
        .value_kind:     hidden_multigrid_sync_arg
      - .offset:         320
        .size:           4
        .value_kind:     hidden_dynamic_lds_size
    .group_segment_fixed_size: 0
    .kernarg_segment_align: 8
    .kernarg_segment_size: 456
    .language:       OpenCL C
    .language_version:
      - 2
      - 0
    .max_flat_workgroup_size: 512
    .name:           _Z4mega6Params
    .private_segment_fixed_size: 0
    .sgpr_count:     106
    .sgpr_spill_count: 28
    .symbol:         _Z4mega6Params.kd
    .uniform_work_group_size: 1
    .uses_dynamic_stack: false
    .vgpr_count:     256
    .vgpr_spill_count: 0
    .wavefront_size: 64
